# v66 + MLA steady step: second group of V fragment reads issued progressively (each behind the QK MFMA after the one that consumed its K fragment) instead of all after QK MFMA 11
# baseline (speedup 1.0000x reference)
.LBB0_1478:
	s_waitcnt lgkmcnt(9)
	v_mfma_f32_32x32x16_bf16 v[66:81], v[162:165], v[106:109], v[66:81]
	s_waitcnt lgkmcnt(8)
	v_mfma_f32_32x32x16_bf16 v[82:97], v[150:153], v[106:109], v[82:97]
	s_add_u32 s26, s0, s24
	s_addc_u32 s27, s53, s25
	s_lshl_b32 s51, s57, 13
	s_add_i32 s98, s51, s43
	s_mov_b32 s99, m0
	s_mov_b32 m0, s98
	s_nop 0
	global_load_lds_dwordx4 v181, s[26:27]
	s_mov_b32 m0, s99
	s_waitcnt lgkmcnt(7)
	v_mfma_f32_32x32x16_bf16 v[66:81], v[146:149], v[102:105], v[66:81]
	s_waitcnt lgkmcnt(6)
	v_mfma_f32_32x32x16_bf16 v[82:97], v[142:145], v[102:105], v[82:97]
	s_waitcnt lgkmcnt(5)
	v_mfma_f32_32x32x16_bf16 v[66:81], v[138:141], v[114:117], v[66:81]
	ds_read_b64_tr_b16 v[150:151], v158 offset:24576
	ds_read_b64_tr_b16 v[152:153], v158 offset:25088
	ds_read_b64_tr_b16 v[146:147], v158 offset:25600
	ds_read_b64_tr_b16 v[148:149], v158 offset:26112
	ds_read_b64_tr_b16 v[142:143], v158 offset:26624
	ds_read_b64_tr_b16 v[144:145], v158 offset:27136
	ds_read_b64_tr_b16 v[138:139], v158 offset:27648
	ds_read_b64_tr_b16 v[140:141], v158 offset:28160
	s_waitcnt lgkmcnt(12)
	v_mfma_f32_32x32x16_bf16 v[82:97], v[134:137], v[114:117], v[82:97]
	s_waitcnt lgkmcnt(11)
	v_mfma_f32_32x32x16_bf16 v[66:81], v[130:133], v[110:113], v[66:81]
	ds_read_b64_tr_b16 v[134:135], v158 offset:28672
	ds_read_b64_tr_b16 v[136:137], v158 offset:29184
	s_waitcnt lgkmcnt(12)
	v_mfma_f32_32x32x16_bf16 v[82:97], v[126:129], v[110:113], v[82:97]
	ds_read_b64_tr_b16 v[130:131], v158 offset:29696
	ds_read_b64_tr_b16 v[132:133], v158 offset:30208
	s_waitcnt lgkmcnt(13)
	v_mfma_f32_32x32x16_bf16 v[66:81], v[122:125], v[118:121], v[66:81]
	ds_read_b64_tr_b16 v[126:127], v158 offset:30720
	ds_read_b64_tr_b16 v[128:129], v158 offset:31232
	s_waitcnt lgkmcnt(14)
	v_mfma_f32_32x32x16_bf16 v[82:97], v[154:157], v[118:121], v[82:97]
	ds_read_b64_tr_b16 v[122:123], v158 offset:31744
	ds_read_b64_tr_b16 v[124:125], v158 offset:32256
	s_cmp_lg_u32 s101, 0
	s_cbranch_scc0 .Lmla2_slow
	s_nop 4
.LBB0_1482:
	v_exp_f32_e32 v66, v66
	v_exp_f32_e32 v67, v67
	v_exp_f32_e32 v68, v68
	v_exp_f32_e32 v69, v69
	v_exp_f32_e32 v70, v70
	v_exp_f32_e32 v71, v71
	v_exp_f32_e32 v72, v72
	v_exp_f32_e32 v73, v73
	v_cvt_pk_bf16_f32 v154, v66, v67
	v_cvt_pk_bf16_f32 v155, v68, v69
	v_cvt_pk_bf16_f32 v156, v70, v71
	v_cvt_pk_bf16_f32 v157, v72, v73
	v_exp_f32_e32 v74, v74
	v_exp_f32_e32 v75, v75
	s_waitcnt lgkmcnt(14)
	v_mfma_f32_32x32x16_bf16 v[18:33], v[154:157], v[150:153], v[18:33]
	v_exp_f32_e32 v76, v76
	v_exp_f32_e32 v77, v77
	v_exp_f32_e32 v78, v78
	s_waitcnt lgkmcnt(6)
	v_mfma_f32_32x32x16_bf16 v[34:49], v[154:157], v[134:137], v[34:49]
	v_exp_f32_e32 v79, v79
	v_exp_f32_e32 v80, v80
	v_exp_f32_e32 v81, v81
	v_pk_add_f32 v[162:163], v[66:67], v[68:69]
	v_pk_add_f32 v[164:165], v[70:71], v[72:73]
	v_pk_add_f32 v[158:159], v[162:163], v[164:165]
	v_pk_add_f32 v[154:155], v[74:75], v[76:77]
	v_pk_add_f32 v[156:157], v[78:79], v[80:81]
	v_pk_add_f32 v[160:161], v[154:155], v[156:157]
	v_cvt_pk_bf16_f32 v70, v74, v75
	v_cvt_pk_bf16_f32 v71, v76, v77
	v_cvt_pk_bf16_f32 v72, v78, v79
	v_cvt_pk_bf16_f32 v73, v80, v81
	v_exp_f32_e32 v82, v82
	v_exp_f32_e32 v83, v83
	v_mfma_f32_32x32x16_bf16 v[18:33], v[70:73], v[146:149], v[18:33]
	v_exp_f32_e32 v84, v84
	v_exp_f32_e32 v85, v85
	v_exp_f32_e32 v86, v86
	s_waitcnt lgkmcnt(4)
	v_mfma_f32_32x32x16_bf16 v[34:49], v[70:73], v[130:133], v[34:49]
	v_exp_f32_e32 v87, v87
	v_exp_f32_e32 v88, v88
	v_exp_f32_e32 v89, v89
	v_pk_add_f32 v[154:155], v[82:83], v[84:85]
	v_pk_add_f32 v[156:157], v[86:87], v[88:89]
	v_pk_add_f32 v[162:163], v[154:155], v[156:157]
	v_cvt_pk_bf16_f32 v74, v82, v83
	v_cvt_pk_bf16_f32 v75, v84, v85
	v_cvt_pk_bf16_f32 v76, v86, v87
	v_cvt_pk_bf16_f32 v77, v88, v89
	v_exp_f32_e32 v90, v90
	v_exp_f32_e32 v91, v91
	v_mfma_f32_32x32x16_bf16 v[18:33], v[74:77], v[142:145], v[18:33]
	v_exp_f32_e32 v92, v92
	v_exp_f32_e32 v93, v93
	v_exp_f32_e32 v94, v94
	s_waitcnt lgkmcnt(2)
	v_mfma_f32_32x32x16_bf16 v[34:49], v[74:77], v[126:129], v[34:49]
	v_exp_f32_e32 v95, v95
	v_exp_f32_e32 v96, v96
	v_exp_f32_e32 v97, v97
	v_pk_add_f32 v[154:155], v[90:91], v[92:93]
	v_pk_add_f32 v[156:157], v[94:95], v[96:97]
	v_pk_add_f32 v[164:165], v[154:155], v[156:157]
	v_cvt_pk_bf16_f32 v78, v90, v91
	v_cvt_pk_bf16_f32 v79, v92, v93
	v_cvt_pk_bf16_f32 v80, v94, v95
	v_cvt_pk_bf16_f32 v81, v96, v97
	v_pk_add_f32 v[158:159], v[158:159], v[160:161]
	s_add_u32 s24, s24, 0x10000
	s_addc_u32 s25, s25, 0
	v_mfma_f32_32x32x16_bf16 v[18:33], v[78:81], v[138:141], v[18:33]
	v_pk_add_f32 v[162:163], v[162:163], v[164:165]
	s_add_u32 s22, s22, 0x1000
	s_addc_u32 s23, s23, 0
	s_waitcnt lgkmcnt(0)
	v_mfma_f32_32x32x16_bf16 v[34:49], v[78:81], v[122:125], v[34:49]
	v_pk_add_f32 v[158:159], v[158:159], v[162:163]
	v_add_f32_e32 v158, v158, v159
	v_add_u32_e32 v66, s56, v182
	v_add_f32_e32 v173, v173, v158
	v_add_u32_e32 v67, v66, v184
	v_add_u32_e32 v66, v66, v189
	s_cmp_eq_u32 s24, 0x200000
	s_waitcnt vmcnt(0) lgkmcnt(0)
	s_barrier
	ds_read_b128 v[82:85], v67
	s_cbranch_scc1 .LBB0_1484
	s_mov_b32 s49, s57
	s_mul_i32 s52, s49, 0x3000
	s_branch .Lmla2_reads2
.Lmla2_slow:
	s_nop 4
	v_max_f32_e32 v154, v67, v67
	v_max_f32_e32 v155, v66, v66
	v_max_f32_e32 v154, v155, v154
	s_nop 6
	v_max3_f32 v155, v68, v69, v83
	v_max3_f32 v154, v154, v82, v84
	v_max3_f32 v154, v154, v85, v70
	v_max3_f32 v155, v155, v72, v73
	v_max3_f32 v154, v154, v71, v86
	v_max3_f32 v155, v155, v88, v89
	v_max3_f32 v154, v154, v87, v74
	v_max3_f32 v155, v155, v76, v77
	v_max3_f32 v154, v154, v75, v90
	v_max3_f32 v155, v155, v92, v93
	v_max3_f32 v154, v154, v91, v78
	v_max3_f32 v155, v155, v80, v81
	v_max3_f32 v154, v154, v79, v94
	v_max3_f32 v155, v155, v96, v97
	v_max3_f32 v154, v154, v95, v155
	v_mov_b32_e32 v155, v154
	s_nop 1
	v_permlane32_swap_b32_e32 v154, v155
	v_max_f32_e32 v155, v155, v155
	v_max_f32_e32 v154, v154, v154
	v_max_f32_e32 v154, v154, v155
	v_cmp_lt_f32_e32 vcc, s47, v154
	s_cbranch_vccz .LBB0_1482
	v_max_f32_e32 v50, v154, v154
	v_max_f32_e32 v154, 0, v50
	v_exp_f32_e64 v155, -v154
	v_add_f32_e32 v171, v171, v154
	v_xor_b32_e32 v50, 0x80000000, v171
	v_mov_b32_e32 v51, v50
	v_mov_b32_e32 v52, v50
	v_mov_b32_e32 v53, v50
	v_mov_b32_e32 v54, v50
	v_mov_b32_e32 v55, v50
	v_mov_b32_e32 v56, v50
	v_mov_b32_e32 v57, v50
	v_mov_b32_e32 v58, v50
	v_mov_b32_e32 v59, v50
	v_mov_b32_e32 v60, v50
	v_mov_b32_e32 v61, v50
	v_mov_b32_e32 v62, v50
	v_mov_b32_e32 v63, v50
	v_mov_b32_e32 v64, v50
	v_mov_b32_e32 v65, v50
	s_and_saveexec_b64 s[26:27], s[6:7]
	ds_write_b32 v186, v155 offset:40960
	s_or_b64 exec, exec, s[26:27]
	v_add_u32_e32 v164, s42, v187
	ds_read_b128 v[156:159], v164 offset:41024
	ds_read_b128 v[160:163], v164 offset:41056
	ds_read_b128 v[196:199], v164 offset:40960
	ds_read_b128 v[200:203], v164 offset:40992
	v_pk_add_f32 v[66:67], v[66:67], v[154:155] op_sel_hi:[1,0] neg_lo:[0,1] neg_hi:[0,1]
	v_pk_add_f32 v[82:83], v[82:83], v[154:155] op_sel_hi:[1,0] neg_lo:[0,1] neg_hi:[0,1]
	v_pk_add_f32 v[68:69], v[68:69], v[154:155] op_sel_hi:[1,0] neg_lo:[0,1] neg_hi:[0,1]
	v_pk_add_f32 v[84:85], v[84:85], v[154:155] op_sel_hi:[1,0] neg_lo:[0,1] neg_hi:[0,1]
	v_pk_add_f32 v[70:71], v[70:71], v[154:155] op_sel_hi:[1,0] neg_lo:[0,1] neg_hi:[0,1]
	v_pk_add_f32 v[86:87], v[86:87], v[154:155] op_sel_hi:[1,0] neg_lo:[0,1] neg_hi:[0,1]
	v_pk_add_f32 v[72:73], v[72:73], v[154:155] op_sel_hi:[1,0] neg_lo:[0,1] neg_hi:[0,1]
	v_pk_add_f32 v[88:89], v[88:89], v[154:155] op_sel_hi:[1,0] neg_lo:[0,1] neg_hi:[0,1]
	v_pk_add_f32 v[74:75], v[74:75], v[154:155] op_sel_hi:[1,0] neg_lo:[0,1] neg_hi:[0,1]
	v_pk_add_f32 v[90:91], v[90:91], v[154:155] op_sel_hi:[1,0] neg_lo:[0,1] neg_hi:[0,1]
	v_pk_add_f32 v[76:77], v[76:77], v[154:155] op_sel_hi:[1,0] neg_lo:[0,1] neg_hi:[0,1]
	v_pk_add_f32 v[92:93], v[92:93], v[154:155] op_sel_hi:[1,0] neg_lo:[0,1] neg_hi:[0,1]
	v_pk_add_f32 v[78:79], v[78:79], v[154:155] op_sel_hi:[1,0] neg_lo:[0,1] neg_hi:[0,1]
	v_pk_add_f32 v[94:95], v[94:95], v[154:155] op_sel_hi:[1,0] neg_lo:[0,1] neg_hi:[0,1]
	v_pk_add_f32 v[80:81], v[80:81], v[154:155] op_sel_hi:[1,0] neg_lo:[0,1] neg_hi:[0,1]
	v_pk_add_f32 v[96:97], v[96:97], v[154:155] op_sel_hi:[1,0] neg_lo:[0,1] neg_hi:[0,1]
	v_mul_f32_e32 v173, v173, v155
	s_waitcnt lgkmcnt(2)
	v_pk_mul_f32 v[30:31], v[30:31], v[160:161]
	v_pk_mul_f32 v[26:27], v[26:27], v[156:157]
	s_waitcnt lgkmcnt(0)
	v_pk_mul_f32 v[22:23], v[22:23], v[200:201]
	v_pk_mul_f32 v[32:33], v[32:33], v[162:163]
	v_pk_mul_f32 v[28:29], v[28:29], v[158:159]
	v_pk_mul_f32 v[24:25], v[24:25], v[202:203]
	v_pk_mul_f32 v[20:21], v[20:21], v[198:199]
	v_pk_mul_f32 v[18:19], v[18:19], v[196:197]
	v_pk_mul_f32 v[46:47], v[46:47], v[160:161]
	v_pk_mul_f32 v[42:43], v[42:43], v[156:157]
	v_pk_mul_f32 v[38:39], v[38:39], v[200:201]
	v_pk_mul_f32 v[48:49], v[48:49], v[162:163]
	v_pk_mul_f32 v[44:45], v[44:45], v[158:159]
	v_pk_mul_f32 v[40:41], v[40:41], v[202:203]
	v_pk_mul_f32 v[36:37], v[36:37], v[198:199]
	v_pk_mul_f32 v[34:35], v[34:35], v[196:197]
	s_branch .LBB0_1482
